# a35: .p2align 6 on attention L and E loop heads (code placement pin)
# speedup vs baseline: 1.0134x; 1.0134x over previous
.LBB0_627:
	s_mov_b64 s[44:45], -1
	s_and_b64 vcc, exec, s[18:19]
	s_cbranch_vccz .LBB0_631
	v_mbcnt_lo_u32_b32 v0, -1, 0
	v_mbcnt_hi_u32_b32 v0, -1, v0
	s_nop 3
	v_mov_b64_e32 v[2:3], s[0:1]
	v_add_u32_e32 v1, s33, v0
	v_and_b32_e32 v168, 31, v0
	v_bfe_u32 v172, v0, 5, 1
	v_ashrrev_i32_e32 v0, 1, v1
	v_and_b32_e32 v170, 0xffffffe0, v0
	v_ashrrev_i32_e32 v171, 31, v170
	v_or_b32_e32 v0, s42, v168
	v_mov_b32_e32 v1, s43
	v_lshl_add_u64 v[0:1], v[0:1], 0, v[170:171]
	v_mad_u64_u32 v[2:3], s[8:9], v0, s35, v[2:3]
	v_mov_b32_e32 v0, v3
	v_mad_u64_u32 v[0:1], s[8:9], v1, s35, v[0:1]
	v_mov_b32_e32 v3, v0
	v_lshlrev_b32_e32 v0, 4, v172
	v_mov_b32_e32 v1, v169
	v_lshl_add_u64 v[2:3], v[2:3], 0, v[0:1]
	global_load_dwordx4 v[64:67], v[2:3], off
	global_load_dwordx4 v[68:71], v[2:3], off offset:32
	global_load_dwordx4 v[72:75], v[2:3], off offset:64
	global_load_dwordx4 v[76:79], v[2:3], off offset:96
	global_load_dwordx4 v[80:83], v[2:3], off offset:128
	global_load_dwordx4 v[84:87], v[2:3], off offset:160
	v_mul_u32_u24_e32 v1, 0xd0, v168
	v_add3_u32 v89, 0, v1, v0
	s_barrier
	ds_read_b128 v[0:3], v89
	ds_read_b128 v[4:7], v89 offset:32
	ds_read_b128 v[8:11], v89 offset:6656
	ds_read_b128 v[12:15], v89 offset:6688
	ds_read_b128 v[16:19], v89 offset:64
	ds_read_b128 v[20:23], v89 offset:96
	ds_read_b128 v[24:27], v89 offset:6720
	ds_read_b128 v[28:31], v89 offset:6752
	ds_read_b128 v[90:93], v89 offset:128
	ds_read_b128 v[94:97], v89 offset:160
	ds_read_b128 v[98:101], v89 offset:6784
	ds_read_b128 v[102:105], v89 offset:6816
	s_mov_b32 s22, 1
	s_setprio 1
	s_waitcnt vmcnt(5) lgkmcnt(11)
	v_mfma_f32_32x32x16_bf16 v[48:63], v[0:3], v[64:67], 0
	s_mov_b32 s8, 0
	s_waitcnt lgkmcnt(9)
	v_mfma_f32_32x32x16_bf16 v[32:47], v[8:11], v[64:67], 0
	s_waitcnt vmcnt(4)
	v_mfma_f32_32x32x16_bf16 v[48:63], v[4:7], v[68:71], v[48:63]
	s_waitcnt lgkmcnt(8)
	v_mfma_f32_32x32x16_bf16 v[32:47], v[12:15], v[68:71], v[32:47]
	s_waitcnt vmcnt(3) lgkmcnt(7)
	v_mfma_f32_32x32x16_bf16 v[48:63], v[16:19], v[72:75], v[48:63]
	s_waitcnt lgkmcnt(5)
	v_mfma_f32_32x32x16_bf16 v[32:47], v[24:27], v[72:75], v[32:47]
	s_waitcnt vmcnt(2)
	v_mfma_f32_32x32x16_bf16 v[48:63], v[20:23], v[76:79], v[48:63]
	s_waitcnt lgkmcnt(4)
	v_mfma_f32_32x32x16_bf16 v[32:47], v[28:31], v[76:79], v[32:47]
	s_waitcnt vmcnt(1) lgkmcnt(3)
	v_mfma_f32_32x32x16_bf16 v[48:63], v[90:93], v[80:83], v[48:63]
	s_waitcnt lgkmcnt(1)
	v_mfma_f32_32x32x16_bf16 v[32:47], v[98:101], v[80:83], v[32:47]
	s_waitcnt vmcnt(0)
	v_mfma_f32_32x32x16_bf16 v[48:63], v[94:97], v[84:87], v[48:63]
	s_waitcnt lgkmcnt(0)
	v_mfma_f32_32x32x16_bf16 v[32:47], v[102:105], v[84:87], v[32:47]
	s_setprio 0
	v_lshlrev_b32_e32 v0, 6, v168
	v_mov_b32_e32 v88, 0
	v_sub_u32_e32 v90, v89, v0
	s_mov_b32 s44, 2
	s_mov_b32 s9, 0
	v_mov_b32_e32 v16, 0
	v_mov_b32_e32 v17, v88
	v_mov_b32_e32 v18, v88
	v_mov_b32_e32 v19, v88
	v_mov_b32_e32 v20, v88
	v_mov_b32_e32 v21, v88
	v_mov_b32_e32 v22, v88
	v_mov_b32_e32 v23, v88
	v_mov_b32_e32 v24, v88
	v_mov_b32_e32 v25, v88
	v_mov_b32_e32 v26, v88
	v_mov_b32_e32 v27, v88
	v_mov_b32_e32 v28, v88
	v_mov_b32_e32 v29, v88
	v_mov_b32_e32 v30, v88
	v_mov_b32_e32 v31, v88
	v_mov_b32_e32 v0, 0
	v_mov_b32_e32 v1, v88
	v_mov_b32_e32 v2, v88
	v_mov_b32_e32 v3, v88
	v_mov_b32_e32 v4, v88
	v_mov_b32_e32 v5, v88
	v_mov_b32_e32 v6, v88
	v_mov_b32_e32 v7, v88
	v_mov_b32_e32 v8, v88
	v_mov_b32_e32 v9, v88
	v_mov_b32_e32 v10, v88
	v_mov_b32_e32 v11, v88
	v_mov_b32_e32 v12, v88
	v_mov_b32_e32 v13, v88
	v_mov_b32_e32 v14, v88
	v_mov_b32_e32 v15, v88
	.p2align	6

.LBB0_631:
	s_and_b64 vcc, exec, s[44:45]
	s_cbranch_vccz .LBB0_592
	s_add_i32 s8, s60, 2
	s_add_i32 s9, s40, 0x2000
	s_mul_i32 s41, s38, 0x180000
	s_lshl_b64 s[46:47], s[38:39], 20
	s_mul_hi_i32 s22, s38, 0x180000
	s_add_u32 s44, s6, s41
	v_mbcnt_lo_u32_b32 v39, -1, 0
	v_mbcnt_hi_u32_b32 v39, -1, v39
	s_addc_u32 s45, s7, s22
	v_add_u32_e32 v32, s33, v39
	s_mul_i32 s59, s59, 0xc000
	v_and_b32_e32 v40, 0xff, v32
	s_add_u32 s60, s44, s59
	v_lshlrev_b32_e32 v36, 4, v40
	v_mov_b32_e32 v37, v169
	s_addc_u32 s61, s45, 0
	v_lshl_add_u64 v[28:29], s[60:61], 0, v[36:37]
	v_add_co_u32_e32 v8, vcc, s54, v28
	s_add_u32 s46, s12, s46
	v_lshlrev_b32_e32 v0, 7, v39
	v_addc_co_u32_e32 v9, vcc, 0, v29, vcc
	s_addc_u32 s47, s13, s47
	v_bfe_u32 v41, v32, 6, 2
	v_and_b32_e32 v12, 0x1f80, v0
	global_load_dwordx4 v[0:3], v36, s[60:61]
	s_add_u32 s60, s46, s40
	v_add_co_u32_e32 v24, vcc, s55, v28
	v_lshl_or_b32 v38, v41, 4, v12
	s_addc_u32 s61, s47, 0
	v_addc_co_u32_e32 v25, vcc, 0, v29, vcc
	global_load_dwordx4 v[4:7], v[8:9], off offset:-4096
	s_nop 0
	global_load_dwordx4 v[8:11], v[8:9], off
	s_nop 0
	global_load_dwordx4 v[12:15], v38, s[60:61]
	global_load_dwordx4 v[16:19], v38, s[60:61] offset:64
	global_load_dwordx4 v[20:23], v[24:25], off offset:-4096
	s_nop 0
	global_load_dwordx4 v[24:27], v[24:25], off
	v_ashrrev_i32_e32 v32, 1, v32
	v_and_b32_e32 v168, 31, v39
	v_and_b32_e32 v170, 0xffffffe0, v32
	v_ashrrev_i32_e32 v171, 31, v170
	v_or_b32_e32 v32, s42, v168
	v_mov_b32_e32 v33, s43
	v_lshl_add_u64 v[32:33], v[32:33], 0, v[170:171]
	v_mov_b64_e32 v[34:35], s[0:1]
	v_mad_u64_u32 v[34:35], s[42:43], v32, s35, v[34:35]
	v_mov_b32_e32 v32, v35
	v_bfe_u32 v172, v39, 5, 1
	v_mad_u64_u32 v[32:33], s[42:43], v33, s35, v[32:33]
	v_add_co_u32_e32 v28, vcc, s56, v28
	v_mov_b32_e32 v35, v32
	v_lshlrev_b32_e32 v32, 4, v172
	v_mov_b32_e32 v33, v169
	v_addc_co_u32_e32 v29, vcc, 0, v29, vcc
	v_lshl_add_u64 v[34:35], v[34:35], 0, v[32:33]
	global_load_dwordx4 v[28:31], v[28:29], off
	s_nop 0
	global_load_dwordx4 v[84:87], v[34:35], off
	global_load_dwordx4 v[80:83], v[34:35], off offset:32
	global_load_dwordx4 v[76:79], v[34:35], off offset:64
	global_load_dwordx4 v[72:75], v[34:35], off offset:96
	global_load_dwordx4 v[68:71], v[34:35], off offset:128
	global_load_dwordx4 v[64:67], v[34:35], off offset:160
	v_mul_lo_u16_e32 v33, 0xab, v40
	v_lshrrev_b16_e32 v33, 11, v33
	v_add_lshl_u32 v160, v40, v33, 4
	v_or_b32_e32 v33, 0x100, v40
	v_mul_u32_u24_e32 v34, 0x1556, v33
	v_lshrrev_b32_e32 v34, 16, v34
	v_add_lshl_u32 v161, v33, v34, 4
	v_or_b32_e32 v33, 0x200, v40
	v_mul_u32_u24_e32 v34, 0x1556, v33
	v_lshrrev_b32_e32 v34, 16, v34
	v_add_lshl_u32 v162, v33, v34, 4
	v_lshrrev_b32_e32 v34, 1, v39
	v_lshlrev_b32_e32 v35, 1, v39
	v_and_b32_e32 v33, 51, v39
	v_and_b32_e32 v34, 4, v34
	v_and_b32_e32 v35, 8, v35
	v_or3_b32 v33, v33, v34, v35
	v_lshlrev_b32_e32 v33, 1, v33
	v_mul_u32_u24_e32 v34, 0x480, v41
	v_add_u32_e32 v35, 0, v160
	v_add3_u32 v156, 0, v33, v34
	v_mov_b32_e32 v39, v169
	v_mov_b32_e32 v159, 0
	s_mov_b32 s59, 2
	s_mov_b32 s39, 1
	s_mov_b32 s41, 0
	v_lshl_add_u64 v[154:155], s[44:45], 0, v[36:37]
	v_lshl_add_u64 v[152:153], s[46:47], 0, v[38:39]
	s_mov_b32 s42, 0
	s_waitcnt vmcnt(13)
	ds_write_b128 v35, v[0:3]
	v_add_u32_e32 v0, 0, v161
	v_add_u32_e32 v1, 0, v162
	v_mov_b32_e32 v2, v159
	v_mov_b32_e32 v3, v159
	s_waitcnt vmcnt(12)
	ds_write_b128 v0, v[4:7]
	s_waitcnt vmcnt(11)
	ds_write_b128 v1, v[8:11]
	s_waitcnt vmcnt(10)
	ds_write_b16 v156, v12 offset:39936
	ds_write_b16_d16_hi v156, v12 offset:40080
	ds_write_b16 v156, v13 offset:40224
	ds_write_b16_d16_hi v156, v13 offset:40368
	ds_write_b16 v156, v14 offset:40512
	ds_write_b16_d16_hi v156, v14 offset:40656
	ds_write_b16 v156, v15 offset:40800
	ds_write_b16_d16_hi v156, v15 offset:40944
	s_waitcnt vmcnt(9)
	ds_write_b16 v156, v16 offset:44544
	ds_write_b16_d16_hi v156, v16 offset:44688
	ds_write_b16 v156, v17 offset:44832
	ds_write_b16_d16_hi v156, v17 offset:44976
	ds_write_b16 v156, v18 offset:45120
	ds_write_b16_d16_hi v156, v18 offset:45264
	ds_write_b16 v156, v19 offset:45408
	ds_write_b16_d16_hi v156, v19 offset:45552
	s_waitcnt vmcnt(8)
	ds_write_b128 v35, v[20:23] offset:13312
	s_waitcnt vmcnt(7)
	ds_write_b128 v0, v[24:27] offset:13312
	s_waitcnt vmcnt(6)
	ds_write_b128 v1, v[28:31] offset:13312
	v_mul_u32_u24_e32 v0, 0xd0, v168
	v_add3_u32 v158, 0, v0, v32
	s_waitcnt lgkmcnt(0)
	s_barrier
	ds_read_b128 v[32:35], v158
	ds_read_b128 v[116:119], v158 offset:32
	ds_read_b128 v[128:131], v158 offset:6656
	ds_read_b128 v[124:127], v158 offset:6688
	ds_read_b128 v[112:115], v158 offset:64
	ds_read_b128 v[100:103], v158 offset:96
	ds_read_b128 v[108:111], v158 offset:6720
	ds_read_b128 v[104:107], v158 offset:6752
	ds_read_b128 v[92:95], v158 offset:128
	ds_read_b128 v[88:91], v158 offset:160
	ds_read_b128 v[120:123], v158 offset:6784
	ds_read_b128 v[96:99], v158 offset:6816
	v_lshlrev_b32_e32 v0, 6, v168
	v_sub_u32_e32 v157, v158, v0
	v_mov_b32_e32 v16, 0
	v_mov_b32_e32 v17, v159
	v_mov_b32_e32 v18, v159
	v_mov_b32_e32 v19, v159
	v_mov_b32_e32 v20, v159
	v_mov_b32_e32 v21, v159
	v_mov_b32_e32 v22, v159
	v_mov_b32_e32 v23, v159
	v_mov_b32_e32 v24, v159
	v_mov_b32_e32 v25, v159
	v_mov_b32_e32 v26, v159
	v_mov_b32_e32 v27, v159
	v_mov_b32_e32 v28, v159
	v_mov_b32_e32 v29, v159
	v_mov_b32_e32 v30, v159
	v_mov_b32_e32 v31, v159
	v_mov_b32_e32 v0, 0
	v_mov_b32_e32 v1, v159
	v_mov_b32_e32 v4, v159
	v_mov_b32_e32 v5, v159
	v_mov_b32_e32 v6, v159
	v_mov_b32_e32 v7, v159
	v_mov_b32_e32 v8, v159
	v_mov_b32_e32 v9, v159
	v_mov_b32_e32 v10, v159
	v_mov_b32_e32 v11, v159
	v_mov_b32_e32 v12, v159
	v_mov_b32_e32 v13, v159
	v_mov_b32_e32 v14, v159
	v_mov_b32_e32 v15, v159
	v_mov_b32_e32 v163, v159
	v_mov_b32_e32 v173, v159
	v_mov_b32_e32 v190, v159
	v_mov_b32_e32 v191, v159
	v_mov_b32_e32 v192, v159
	v_mov_b32_e32 v193, v159
	v_mov_b32_e32 v194, v159
	v_mov_b32_e32 v195, v159
	v_mov_b32_e32 v196, v159
	v_mov_b32_e32 v197, v159
	v_mov_b32_e32 v198, v159
	v_mov_b32_e32 v199, v159
	v_mov_b32_e32 v200, v159
	v_mov_b32_e32 v201, v159
	v_mov_b32_e32 v202, v159
	v_mov_b32_e32 v203, v159
	v_mov_b32_e32 v204, v159
	v_mov_b32_e32 v205, v159
	v_mov_b32_e32 v206, v159
	v_mov_b32_e32 v207, v159
	v_mov_b32_e32 v208, v159
	v_mov_b32_e32 v209, v159
	v_mov_b32_e32 v210, v159
	v_mov_b32_e32 v211, v159
	v_mov_b32_e32 v212, v159
	v_mov_b32_e32 v213, v159
	v_mov_b32_e32 v214, v159
	v_mov_b32_e32 v215, v159
	v_mov_b32_e32 v216, v159
	v_mov_b32_e32 v217, v159
	v_mov_b32_e32 v218, v159
	v_mov_b32_e32 v219, v159
	.p2align	6
